# P7 GLA-norm loop: all 8-byte loads/stores widened to 16 bytes via lane-pair DPP exchange (VGPR alloc 256)
# speedup vs baseline: 1.0197x; 1.0149x over previous
; __device__ __forceinline__ unsigned pk2(float lo, float hi) { f32x2_t v = {lo, hi}; bf16x2_t b = __builtin_convertvector(v, bf16x2_t); return __builtin_bit_cast(unsigned, b); }
; __device__ __forceinline__ float fast_silu(float g) { return g * __builtin_amdgcn_rcpf(1.f + __expf(-g)); }
; __global__ void __launch_bounds__(512, 2) mega_fwd(Args args) {
;     ...
;             const f32x4 gg = *(const f32x4*)(args.in[17] + lane * 4);
;             for (int m = gw; m < T; m += NGW) {
;                 u32x2 u[4], zu[4];
; #pragma unroll
;                 for (int h = 0; h < 4; ++h) {
;                     u[h] = *(const u32x2*)(OG + (size_t)(((m >> 11) * 4 + h) * 8 + (lane >> 3)) * (SEQ * 32) + (size_t)(m & 2047) * 32 + (lane & 7) * 4);
;                     zu[h] = *(const u32x2*)(Z + (size_t)m * ZLD + ZZR + h * 256 + lane * 4); }
; #pragma unroll
;                 for (int h = 0; h < 4; ++h) {
;                     const float v0 = bflo(u[h].x), v1 = bfhi(u[h].x), v2 = bflo(u[h].y), v3 = bfhi(u[h].y);
;                     const float r = rsqrtf(wave_sum(v0 * v0 + v1 * v1 + v2 * v2 + v3 * v3) * (1.f / 256.f) + EPS);
;                     const float z0 = bflo(zu[h].x), z1 = bfhi(zu[h].x), z2 = bflo(zu[h].y), z3 = bfhi(zu[h].y);
;                     u32x2 w; w.x = pk2(v0 * r * gg.x * fast_silu(z0), v1 * r * gg.y * fast_silu(z1));
;                     w.y = pk2(v2 * r * gg.z * fast_silu(z2), v3 * r * gg.w * fast_silu(z3));
;                     *(u32x2*)(CAT + (size_t)m * 2048 + 1024 + h * 256 + lane * 4) = w;
;                 }
;             }
.LBB0_1050:
	s_cmp_lt_i32 s92, 8
	s_cselect_b64 s[2:3], -1, 0
	s_and_b64 s[60:61], s[2:3], s[0:1]
	s_andn2_b64 vcc, exec, s[60:61]
	s_cbranch_vccnz .LBB0_1131
	s_cmpk_gt_i32 s82, 0x3fff
	s_cbranch_scc1 .LBB0_1054
	v_readlane_b32 s44, v238, 21
	v_lshlrev_b32_e32 v0, 4, v184
	v_readlane_b32 s46, v238, 23
	v_readlane_b32 s47, v238, 24
	s_ashr_i32 s83, s82, 31
	s_lshl_b64 s[0:1], s[82:83], 12
	s_add_u32 s12, s86, s0
	s_addc_u32 s13, s87, s1
	s_ashr_i32 s97, s96, 31
	global_load_dwordx4 v[0:3], v0, s[46:47]
	s_lshl_b64 s[24:25], s[96:97], 12
	s_mul_i32 s1, s82, 0x1800
	s_mul_hi_i32 s0, s82, 0x1800
	s_add_u32 s26, s86, s1
	s_waitcnt vmcnt(0)
	v_lshlrev_b32_e32 v4, 3, v185
	s_addc_u32 s27, s87, s0
	s_lshl_b32 s0, s80, 8
	s_lshl_b32 s1, s90, 5
	v_lshrrev_b32_e32 v14, 3, v184
	v_and_b32_e32 v4, 56, v4
	v_mov_b32_e32 v5, 0
	s_add_i32 s17, s0, s1
	s_mov_b32 s0, 0x358637bd
	v_lshl_add_u64 v[6:7], s[4:5], 0, v[4:5]
	v_or_b32_e32 v15, 8, v14
	v_or_b32_e32 v16, 16, v14
	v_or_b32_e32 v17, 24, v14
	v_lshlrev_b32_e32 v4, 3, v184
	v_and_b32_e32 v252, 1, v184
	v_mov_b32_e32 v253, 0
	v_mov_b32_e32 v255, 0
	v_mul_u32_u24_e32 v254, 0xffff8, v252
	v_mul_u32_u24_e32 v252, 0x1f8, v252
	s_mul_hi_i32 s14, s96, 0x1800
	s_mul_i32 s16, s96, 0x1800
	s_lshl_b32 s22, s15, 8
	s_mov_b32 s29, 0
	s_mov_b32 s23, 0xa800000
	s_mov_b32 s33, 0xa801000
	s_mov_b32 s36, 0x3b800000
	v_mov_b64_e32 v[8:9], s[0:1]
	s_mov_b32 s34, 0x800000
	s_mov_b32 s35, 0x6800000
	s_mov_b32 s37, s82
	v_readlane_b32 s45, v238, 22
	v_readlane_b32 s48, v238, 25
	v_readlane_b32 s49, v238, 26
	v_readlane_b32 s50, v238, 27
	v_readlane_b32 s51, v238, 28
	v_readlane_b32 s52, v238, 29
	v_readlane_b32 s53, v238, 30
	v_readlane_b32 s54, v238, 31
	v_readlane_b32 s55, v238, 32
	v_readlane_b32 s56, v238, 33
	v_readlane_b32 s57, v238, 34
	v_readlane_b32 s58, v238, 35
	v_readlane_b32 s59, v238, 36
	v_lshl_add_u64 v[110:111], s[26:27], 0, v[4:5]
	v_add_co_u32_e32 v118, vcc, s23, v110
	s_ashr_i32 s0, s37, 9
	s_nop 0
	v_addc_co_u32_e32 v119, vcc, 0, v111, vcc
	v_add_co_u32_e32 v120, vcc, s33, v110
	v_lshl_add_u64 v[112:113], s[12:13], 0, v[4:5]
	s_nop 0
	v_addc_co_u32_e32 v121, vcc, 0, v111, vcc
	s_and_b32 s1, s17, 0xffe0
	s_lshl_b32 s0, s0, 3
	v_add_co_u32_e32 v110, vcc, s35, v112
	s_lshl_b32 s28, s1, 1
	s_nop 0
	v_addc_co_u32_e32 v111, vcc, 0, v113, vcc
	v_lshl_add_u64 v[118:119], v[118:119], 0, v[252:253]
	v_lshl_add_u64 v[120:121], v[120:121], 0, v[252:253]
	global_load_dwordx4 v[88:91], v[118:119], off offset:3744
	s_nop 0
	s_nop 0
	global_load_dwordx4 v[92:95], v[120:121], off offset:672
	s_nop 0
	s_nop 0
	s_and_b32 s1, s0, 0xffffffe0
	v_or_b32_e32 v126, s0, v17
	v_or_b32_e32 v128, s1, v14
	v_or_b32_e32 v130, s1, v15
	v_or_b32_e32 v132, s1, v16
	v_ashrrev_i32_e32 v127, 31, v126
	v_ashrrev_i32_e32 v129, 31, v128
	v_ashrrev_i32_e32 v131, 31, v130
	v_ashrrev_i32_e32 v133, 31, v132
	v_lshl_add_u64 v[124:125], v[6:7], 0, s[28:29]
	v_lshlrev_b64 v[126:127], 17, v[126:127]
	v_lshlrev_b64 v[128:129], 17, v[128:129]
	v_lshlrev_b64 v[130:131], 17, v[130:131]
	v_lshlrev_b64 v[132:133], 17, v[132:133]
	v_lshl_add_u64 v[126:127], v[124:125], 0, v[126:127]
	v_lshl_add_u64 v[128:129], v[124:125], 0, v[128:129]
	v_lshl_add_u64 v[130:131], v[124:125], 0, v[130:131]
	v_lshl_add_u64 v[124:125], v[124:125], 0, v[132:133]
	v_lshl_add_u64 v[128:129], v[128:129], 0, v[254:255]
	v_lshl_add_u64 v[124:125], v[124:125], 0, v[254:255]
	global_load_dwordx4 v[96:99], v[128:129], off
	s_nop 0
	s_nop 0
	s_nop 0
	global_load_dwordx4 v[100:103], v[124:125], off
	s_nop 0
	s_nop 0
	s_add_i32 s37, s37, s96
	s_add_u32 s12, s12, s24
	s_addc_u32 s13, s13, s25
	s_add_u32 s26, s26, s16
	s_addc_u32 s27, s27, s14
	s_add_i32 s17, s17, s22
	s_cmpk_gt_i32 s37, 0x3fff
	s_cselect_b32 s50, 1, 0
	s_waitcnt vmcnt(0)
	v_and_b32_e32 v246, 1, v184
	v_lshrrev_b32_e32 v247, 1, v184
	v_lshlrev_b32_e32 v246, 9, v246
	v_lshl_add_u32 v246, v247, 4, v246
	v_lshlrev_b32_e32 v247, 3, v184
	v_sub_u32_e32 v246, v246, v247
	v_ashrrev_i32_e32 v247, 31, v246
	s_mov_b32 s62, 0xaaaaaaaa
	s_mov_b32 s63, 0xaaaaaaaa
.LBB0_1053:
	v_mov_b32_dpp v248, v88 quad_perm:[1,0,3,2] row_mask:0xf bank_mask:0xf
	v_mov_b32_dpp v249, v89 quad_perm:[1,0,3,2] row_mask:0xf bank_mask:0xf
	v_mov_b32_dpp v250, v90 quad_perm:[1,0,3,2] row_mask:0xf bank_mask:0xf
	v_mov_b32_dpp v251, v91 quad_perm:[1,0,3,2] row_mask:0xf bank_mask:0xf
	v_cndmask_b32_e64 v12, v88, v250, s[62:63]
	v_cndmask_b32_e64 v13, v89, v251, s[62:63]
	v_cndmask_b32_e64 v18, v248, v90, s[62:63]
	v_cndmask_b32_e64 v19, v249, v91, s[62:63]
	v_mov_b32_dpp v248, v92 quad_perm:[1,0,3,2] row_mask:0xf bank_mask:0xf
	v_mov_b32_dpp v249, v93 quad_perm:[1,0,3,2] row_mask:0xf bank_mask:0xf
	v_mov_b32_dpp v250, v94 quad_perm:[1,0,3,2] row_mask:0xf bank_mask:0xf
	v_mov_b32_dpp v251, v95 quad_perm:[1,0,3,2] row_mask:0xf bank_mask:0xf
	v_cndmask_b32_e64 v22, v92, v250, s[62:63]
	v_cndmask_b32_e64 v23, v93, v251, s[62:63]
	v_cndmask_b32_e64 v20, v248, v94, s[62:63]
	v_cndmask_b32_e64 v21, v249, v95, s[62:63]
	v_mov_b32_dpp v248, v96 quad_perm:[1,0,3,2] row_mask:0xf bank_mask:0xf
	v_mov_b32_dpp v249, v97 quad_perm:[1,0,3,2] row_mask:0xf bank_mask:0xf
	v_mov_b32_dpp v250, v98 quad_perm:[1,0,3,2] row_mask:0xf bank_mask:0xf
	v_mov_b32_dpp v251, v99 quad_perm:[1,0,3,2] row_mask:0xf bank_mask:0xf
	v_cndmask_b32_e64 v28, v96, v250, s[62:63]
	v_cndmask_b32_e64 v29, v97, v251, s[62:63]
	v_cndmask_b32_e64 v30, v248, v98, s[62:63]
	v_cndmask_b32_e64 v31, v249, v99, s[62:63]
	v_mov_b32_dpp v248, v100 quad_perm:[1,0,3,2] row_mask:0xf bank_mask:0xf
	v_mov_b32_dpp v249, v101 quad_perm:[1,0,3,2] row_mask:0xf bank_mask:0xf
	v_mov_b32_dpp v250, v102 quad_perm:[1,0,3,2] row_mask:0xf bank_mask:0xf
	v_mov_b32_dpp v251, v103 quad_perm:[1,0,3,2] row_mask:0xf bank_mask:0xf
	v_cndmask_b32_e64 v24, v100, v250, s[62:63]
	v_cndmask_b32_e64 v25, v101, v251, s[62:63]
	v_cndmask_b32_e64 v26, v248, v102, s[62:63]
	v_cndmask_b32_e64 v27, v249, v103, s[62:63]
	v_mov_b32_e32 v104, v110
	v_mov_b32_e32 v105, v111
	v_lshl_add_u64 v[104:105], v[104:105], 0, v[246:247]
	s_mov_b32 s51, 0
	s_cmp_lg_u32 s50, 0
	s_cbranch_scc1 .Lp7n_nopref
; __device__ __forceinline__ unsigned pk2(float lo, float hi) { f32x2_t v = {lo, hi}; bf16x2_t b = __builtin_convertvector(v, bf16x2_t); return __builtin_bit_cast(unsigned, b); }
; __device__ __forceinline__ float fast_silu(float g) { return g * __builtin_amdgcn_rcpf(1.f + __expf(-g)); }
; __global__ void __launch_bounds__(512, 2) mega_fwd(Args args) {
;     ...
;             for (int m = gw; m < T; m += NGW) {
;                 u32x2 u[4], zu[4];
; #pragma unroll
;                 for (int h = 0; h < 4; ++h) {
;                     u[h] = *(const u32x2*)(OG + (size_t)(((m >> 11) * 4 + h) * 8 + (lane >> 3)) * (SEQ * 32) + (size_t)(m & 2047) * 32 + (lane & 7) * 4);
;                     zu[h] = *(const u32x2*)(Z + (size_t)m * ZLD + ZZR + h * 256 + lane * 4); }
; #pragma unroll
;                 for (int h = 0; h < 4; ++h) {
;                     const float v0 = bflo(u[h].x), v1 = bfhi(u[h].x), v2 = bflo(u[h].y), v3 = bfhi(u[h].y);
;                     const float r = rsqrtf(wave_sum(v0 * v0 + v1 * v1 + v2 * v2 + v3 * v3) * (1.f / 256.f) + EPS);
;                     const float z0 = bflo(zu[h].x), z1 = bfhi(zu[h].x), z2 = bflo(zu[h].y), z3 = bfhi(zu[h].y);
;                     u32x2 w; w.x = pk2(v0 * r * gg.x * fast_silu(z0), v1 * r * gg.y * fast_silu(z1));
;                     w.y = pk2(v2 * r * gg.z * fast_silu(z2), v3 * r * gg.w * fast_silu(z3));
	v_lshl_add_u64 v[110:111], s[26:27], 0, v[4:5]
	v_add_co_u32_e32 v118, vcc, s23, v110
	s_ashr_i32 s0, s37, 9
	s_nop 0
	v_addc_co_u32_e32 v119, vcc, 0, v111, vcc
	v_add_co_u32_e32 v120, vcc, s33, v110
	v_lshl_add_u64 v[112:113], s[12:13], 0, v[4:5]
	s_nop 0
	v_addc_co_u32_e32 v121, vcc, 0, v111, vcc
	s_and_b32 s1, s17, 0xffe0
	s_lshl_b32 s0, s0, 3
	v_add_co_u32_e32 v110, vcc, s35, v112
	s_lshl_b32 s28, s1, 1
	s_nop 0
	v_addc_co_u32_e32 v111, vcc, 0, v113, vcc
	v_lshl_add_u64 v[118:119], v[118:119], 0, v[252:253]
	v_lshl_add_u64 v[120:121], v[120:121], 0, v[252:253]
	global_load_dwordx4 v[88:91], v[118:119], off offset:3744
	s_nop 0
	s_nop 0
	global_load_dwordx4 v[92:95], v[120:121], off offset:672
	s_nop 0
	s_nop 0
	s_and_b32 s1, s0, 0xffffffe0
	v_or_b32_e32 v126, s0, v17
	v_or_b32_e32 v128, s1, v14
	v_or_b32_e32 v130, s1, v15
	v_or_b32_e32 v132, s1, v16
	v_ashrrev_i32_e32 v127, 31, v126
	v_ashrrev_i32_e32 v129, 31, v128
	v_ashrrev_i32_e32 v131, 31, v130
	v_ashrrev_i32_e32 v133, 31, v132
	v_lshl_add_u64 v[124:125], v[6:7], 0, s[28:29]
	v_lshlrev_b64 v[126:127], 17, v[126:127]
	v_lshlrev_b64 v[128:129], 17, v[128:129]
	v_lshlrev_b64 v[130:131], 17, v[130:131]
	v_lshlrev_b64 v[132:133], 17, v[132:133]
	v_lshl_add_u64 v[126:127], v[124:125], 0, v[126:127]
	v_lshl_add_u64 v[128:129], v[124:125], 0, v[128:129]
	v_lshl_add_u64 v[130:131], v[124:125], 0, v[130:131]
	v_lshl_add_u64 v[124:125], v[124:125], 0, v[132:133]
	v_lshl_add_u64 v[128:129], v[128:129], 0, v[254:255]
	v_lshl_add_u64 v[124:125], v[124:125], 0, v[254:255]
	global_load_dwordx4 v[96:99], v[128:129], off
	s_nop 0
	s_nop 0
	s_nop 0
	global_load_dwordx4 v[100:103], v[124:125], off
	s_nop 0
	s_nop 0
	s_add_i32 s37, s37, s96
	s_add_u32 s12, s12, s24
	s_addc_u32 s13, s13, s25
	s_add_u32 s26, s26, s16
	s_addc_u32 s27, s27, s14
	s_add_i32 s17, s17, s22
	s_cmpk_gt_i32 s37, 0x3fff
	s_cselect_b32 s50, 1, 0
	s_mov_b32 s51, 1
.Lp7n_nopref:
	v_lshlrev_b32_e32 v32, 16, v13
	v_and_b32_e32 v33, 0xffff0000, v13
	v_lshlrev_b32_e32 v34, 16, v12
	v_and_b32_e32 v35, 0xffff0000, v12
	v_lshlrev_b32_e32 v12, 16, v19
	v_and_b32_e32 v13, 0xffff0000, v19
	v_lshlrev_b32_e32 v36, 16, v18
	v_and_b32_e32 v37, 0xffff0000, v18
	v_lshlrev_b32_e32 v18, 16, v23
	v_and_b32_e32 v19, 0xffff0000, v23
	v_lshlrev_b32_e32 v38, 16, v22
	v_and_b32_e32 v39, 0xffff0000, v22
	v_lshlrev_b32_e32 v22, 16, v21
	v_and_b32_e32 v23, 0xffff0000, v21
	v_lshlrev_b32_e32 v40, 16, v20
	v_and_b32_e32 v41, 0xffff0000, v20
	v_mul_f32_e32 v20, 0xbfb8aa3b, v34
	v_mul_f32_e32 v21, 0xbfb8aa3b, v35
	v_mul_f32_e32 v42, 0xbfb8aa3b, v32
	v_mul_f32_e32 v43, 0xbfb8aa3b, v33
	v_mul_f32_e32 v44, 0xbfb8aa3b, v36
	v_mul_f32_e32 v45, 0xbfb8aa3b, v37
	v_mul_f32_e32 v46, 0xbfb8aa3b, v12
	v_mul_f32_e32 v47, 0xbfb8aa3b, v13
	v_mul_f32_e32 v48, 0xbfb8aa3b, v38
	v_mul_f32_e32 v49, 0xbfb8aa3b, v39
	v_mul_f32_e32 v52, 0xbfb8aa3b, v40
	v_mul_f32_e32 v53, 0xbfb8aa3b, v41
	v_exp_f32_e32 v56, v20
	v_exp_f32_e32 v57, v21
	v_exp_f32_e32 v58, v42
	v_exp_f32_e32 v59, v43
	v_mul_f32_e32 v50, 0xbfb8aa3b, v18
	v_mul_f32_e32 v51, 0xbfb8aa3b, v19
	v_mul_f32_e32 v54, 0xbfb8aa3b, v22
	v_mul_f32_e32 v55, 0xbfb8aa3b, v23
	v_exp_f32_e32 v60, v44
	v_exp_f32_e32 v61, v45
	v_exp_f32_e32 v62, v46
	v_exp_f32_e32 v63, v47
	v_exp_f32_e32 v64, v48
	v_exp_f32_e32 v65, v49
	v_exp_f32_e32 v68, v52
	v_exp_f32_e32 v69, v53
	v_exp_f32_e32 v66, v50
	v_exp_f32_e32 v67, v51
	v_exp_f32_e32 v70, v54
	v_exp_f32_e32 v71, v55
	v_lshlrev_b32_e32 v42, 16, v28
	v_and_b32_e32 v43, 0xffff0000, v28
	v_lshlrev_b32_e32 v44, 16, v30
	v_and_b32_e32 v45, 0xffff0000, v30
	v_lshlrev_b32_e32 v20, 16, v29
	v_and_b32_e32 v21, 0xffff0000, v29
	v_lshlrev_b32_e32 v28, 16, v31
	v_and_b32_e32 v29, 0xffff0000, v31
	v_lshlrev_b32_e32 v46, 16, v24
	v_and_b32_e32 v47, 0xffff0000, v24
	v_lshlrev_b32_e32 v48, 16, v26
	v_and_b32_e32 v49, 0xffff0000, v26
	v_pk_mul_f32 v[50:51], v[42:43], v[42:43]
	v_add_f32_e32 v72, 1.0, v56
	v_add_f32_e32 v73, 1.0, v57
	v_add_f32_e32 v74, 1.0, v58
	v_add_f32_e32 v75, 1.0, v59
	v_pk_mul_f32 v[54:55], v[44:45], v[44:45]
	v_lshlrev_b32_e32 v30, 16, v25
	v_and_b32_e32 v31, 0xffff0000, v25
	v_lshlrev_b32_e32 v24, 16, v27
	v_and_b32_e32 v25, 0xffff0000, v27
	v_pk_mul_f32 v[26:27], v[20:21], v[20:21]
	v_pk_mul_f32 v[52:53], v[28:29], v[28:29]
	v_add_f32_e32 v76, 1.0, v60
	v_add_f32_e32 v77, 1.0, v61
	v_add_f32_e32 v78, 1.0, v62
	v_add_f32_e32 v79, 1.0, v63
	v_pk_mul_f32 v[58:59], v[46:47], v[46:47]
	v_add_f32_e32 v80, 1.0, v64
	v_add_f32_e32 v81, 1.0, v65
	v_pk_mul_f32 v[62:63], v[48:49], v[48:49]
	v_add_f32_e32 v84, 1.0, v68
	v_add_f32_e32 v85, 1.0, v69
	v_rcp_f32_e32 v64, v72
	v_rcp_f32_e32 v65, v73
	v_add_f32_e32 v72, v50, v51
	v_rcp_f32_e32 v50, v74
	v_rcp_f32_e32 v51, v75
	v_add_f32_e32 v73, v54, v55
	v_pk_mul_f32 v[56:57], v[30:31], v[30:31]
	v_add_f32_e32 v82, 1.0, v66
	v_add_f32_e32 v83, 1.0, v67
	v_pk_mul_f32 v[60:61], v[24:25], v[24:25]
	v_add_f32_e32 v86, 1.0, v70
	v_add_f32_e32 v87, 1.0, v71
	v_rcp_f32_e32 v66, v76
	v_rcp_f32_e32 v67, v77
	v_rcp_f32_e32 v68, v80
	v_rcp_f32_e32 v69, v81
	v_add_f32_e32 v74, v58, v59
	v_rcp_f32_e32 v70, v84
	v_rcp_f32_e32 v71, v85
	v_add_f32_e32 v75, v62, v63
	v_add_f32_e32 v26, v26, v72
	v_add_f32_e32 v52, v52, v73
	v_add_f32_e32 v56, v56, v74
	v_add_f32_e32 v60, v60, v75
	v_add_f32_e32 v26, v27, v26
	v_add_f32_e32 v27, v53, v52
	v_add_f32_e32 v52, v57, v56
	v_add_f32_e32 v53, v61, v60
	v_add_f32_dpp v56, v26, v26 quad_perm:[1,0,3,2] row_mask:0xf bank_mask:0xf bound_ctrl:1
	v_add_f32_dpp v57, v27, v27 quad_perm:[1,0,3,2] row_mask:0xf bank_mask:0xf bound_ctrl:1
	v_add_f32_dpp v52, v52, v52 quad_perm:[1,0,3,2] row_mask:0xf bank_mask:0xf bound_ctrl:1
; __device__ __forceinline__ unsigned pk2(float lo, float hi) { f32x2_t v = {lo, hi}; bf16x2_t b = __builtin_convertvector(v, bf16x2_t); return __builtin_bit_cast(unsigned, b); }
; __device__ __forceinline__ float fast_silu(float g) { return g * __builtin_amdgcn_rcpf(1.f + __expf(-g)); }
; __global__ void __launch_bounds__(512, 2) mega_fwd(Args args) {
;     ...
;                 for (int h = 0; h < 4; ++h) {
;                     const float v0 = bflo(u[h].x), v1 = bfhi(u[h].x), v2 = bflo(u[h].y), v3 = bfhi(u[h].y);
;                     const float r = rsqrtf(wave_sum(v0 * v0 + v1 * v1 + v2 * v2 + v3 * v3) * (1.f / 256.f) + EPS);
;                     const float z0 = bflo(zu[h].x), z1 = bfhi(zu[h].x), z2 = bflo(zu[h].y), z3 = bfhi(zu[h].y);
;                     u32x2 w; w.x = pk2(v0 * r * gg.x * fast_silu(z0), v1 * r * gg.y * fast_silu(z1));
;                     w.y = pk2(v2 * r * gg.z * fast_silu(z2), v3 * r * gg.w * fast_silu(z3));
;                     *(u32x2*)(CAT + (size_t)m * 2048 + 1024 + h * 256 + lane * 4) = w;
;                 }
	v_add_f32_dpp v53, v53, v53 quad_perm:[1,0,3,2] row_mask:0xf bank_mask:0xf bound_ctrl:1
	v_add_f32_dpp v56, v56, v56 quad_perm:[2,3,0,1] row_mask:0xf bank_mask:0xf bound_ctrl:1
	v_pk_mul_f32 v[32:33], v[50:51], v[32:33]
	v_add_f32_dpp v50, v57, v57 quad_perm:[2,3,0,1] row_mask:0xf bank_mask:0xf bound_ctrl:1
	v_rcp_f32_e32 v54, v78
	v_rcp_f32_e32 v55, v79
	v_pk_mul_f32 v[26:27], v[64:65], v[34:35]
	v_pk_mul_f32 v[34:35], v[66:67], v[36:37]
	v_pk_mul_f32 v[36:37], v[68:69], v[38:39]
	v_add_f32_dpp v51, v52, v52 quad_perm:[2,3,0,1] row_mask:0xf bank_mask:0xf bound_ctrl:1
	v_pk_mul_f32 v[38:39], v[70:71], v[40:41]
	v_add_f32_dpp v40, v53, v53 quad_perm:[2,3,0,1] row_mask:0xf bank_mask:0xf bound_ctrl:1
	v_add_f32_dpp v41, v56, v56 row_half_mirror row_mask:0xf bank_mask:0xf bound_ctrl:1
	v_add_f32_dpp v50, v50, v50 row_half_mirror row_mask:0xf bank_mask:0xf bound_ctrl:1
	v_add_f32_dpp v51, v51, v51 row_half_mirror row_mask:0xf bank_mask:0xf bound_ctrl:1
	v_add_f32_dpp v40, v40, v40 row_half_mirror row_mask:0xf bank_mask:0xf bound_ctrl:1
	v_add_f32_dpp v41, v41, v41 row_mirror row_mask:0xf bank_mask:0xf bound_ctrl:1
	v_add_f32_dpp v50, v50, v50 row_mirror row_mask:0xf bank_mask:0xf bound_ctrl:1
	v_add_f32_dpp v51, v51, v51 row_mirror row_mask:0xf bank_mask:0xf bound_ctrl:1
	v_add_f32_dpp v40, v40, v40 row_mirror row_mask:0xf bank_mask:0xf bound_ctrl:1
	v_readlane_b32 s28, v41, 16
	v_readlane_b32 s42, v41, 48
	v_readlane_b32 s43, v50, 16
	v_readlane_b32 s44, v50, 48
	v_readlane_b32 s0, v41, 0
	v_readlane_b32 s1, v41, 32
	v_readlane_b32 s2, v50, 0
	v_readlane_b32 s3, v50, 32
	v_readlane_b32 s4, v51, 0
	v_readlane_b32 s45, v51, 16
	v_readlane_b32 s5, v51, 32
	v_readlane_b32 s46, v51, 48
	v_readlane_b32 s38, v40, 0
	v_readlane_b32 s47, v40, 16
	v_readlane_b32 s39, v40, 32
	v_readlane_b32 s48, v40, 48
	v_mov_b32_e32 v40, s28
	v_mov_b32_e32 v41, s42
	v_mov_b32_e32 v50, s43
	v_mov_b32_e32 v51, s44
	v_pk_mul_f32 v[12:13], v[54:55], v[12:13]
	v_mov_b32_e32 v52, s45
	v_mov_b32_e32 v53, s46
	v_mov_b32_e32 v54, s47
	v_mov_b32_e32 v55, s48
	v_pk_add_f32 v[40:41], s[0:1], v[40:41]
	v_pk_add_f32 v[50:51], s[2:3], v[50:51]
	v_pk_add_f32 v[52:53], s[4:5], v[52:53]
	v_pk_add_f32 v[54:55], s[38:39], v[54:55]
	v_mov_b32_e32 v56, v50
	v_mov_b32_e32 v57, v40
	v_mov_b32_e32 v40, v51
	v_mov_b32_e32 v50, v54
	v_mov_b32_e32 v51, v52
	v_mov_b32_e32 v52, v55
	v_pk_add_f32 v[40:41], v[56:57], v[40:41]
	v_pk_add_f32 v[50:51], v[50:51], v[52:53]
	v_pk_fma_f32 v[40:41], v[40:41], s[36:37], v[8:9] op_sel_hi:[1,0,0]
	v_pk_fma_f32 v[50:51], v[50:51], s[36:37], v[8:9] op_sel_hi:[1,0,0]
	v_mul_f32_e32 v52, 0x4b800000, v41
	v_cmp_gt_f32_e64 s[4:5], s34, v41
	v_mul_f32_e32 v53, 0x4b800000, v40
	v_cmp_gt_f32_e32 vcc, s34, v40
	v_mul_f32_e32 v54, 0x4b800000, v51
	v_mul_f32_e32 v55, 0x4b800000, v50
	v_cmp_gt_f32_e64 s[0:1], s34, v50
	v_cmp_gt_f32_e64 s[2:3], s34, v51
	v_cndmask_b32_e64 v41, v41, v52, s[4:5]
	v_cndmask_b32_e32 v40, v40, v53, vcc
	v_cndmask_b32_e64 v51, v51, v54, s[2:3]
	v_cndmask_b32_e64 v50, v50, v55, s[0:1]
	v_rsq_f32_e32 v41, v41
	v_rsq_f32_e32 v52, v40
	v_rsq_f32_e32 v51, v51
	v_rsq_f32_e32 v53, v50
	v_rcp_f32_e32 v58, v82
	v_rcp_f32_e32 v59, v83
	v_rcp_f32_e32 v62, v86
	v_rcp_f32_e32 v63, v87
	v_mul_f32_e32 v40, 0x45800000, v41
	v_mul_f32_e32 v50, 0x45800000, v52
	v_mul_f32_e32 v54, 0x45800000, v51
	v_mul_f32_e32 v55, 0x45800000, v53
	v_cndmask_b32_e64 v40, v41, v40, s[4:5]
	v_cndmask_b32_e32 v50, v52, v50, vcc
	v_cndmask_b32_e64 v52, v51, v54, s[2:3]
	v_cndmask_b32_e64 v54, v53, v55, s[0:1]
	v_pk_mul_f32 v[42:43], v[40:41], v[42:43] op_sel_hi:[0,1]
	v_pk_mul_f32 v[20:21], v[40:41], v[20:21] op_sel_hi:[0,1]
	v_pk_mul_f32 v[40:41], v[50:51], v[44:45] op_sel_hi:[0,1]
	v_pk_mul_f32 v[28:29], v[50:51], v[28:29] op_sel_hi:[0,1]
	v_pk_mul_f32 v[44:45], v[52:53], v[46:47] op_sel_hi:[0,1]
	v_pk_mul_f32 v[30:31], v[52:53], v[30:31] op_sel_hi:[0,1]
	v_pk_mul_f32 v[46:47], v[54:55], v[48:49] op_sel_hi:[0,1]
	v_pk_mul_f32 v[24:25], v[54:55], v[24:25] op_sel_hi:[0,1]
	v_pk_mul_f32 v[42:43], v[0:1], v[42:43]
	v_pk_mul_f32 v[20:21], v[2:3], v[20:21]
	v_pk_mul_f32 v[18:19], v[58:59], v[18:19]
	v_pk_mul_f32 v[22:23], v[62:63], v[22:23]
	v_pk_mul_f32 v[40:41], v[0:1], v[40:41]
	v_pk_mul_f32 v[28:29], v[2:3], v[28:29]
	v_pk_mul_f32 v[44:45], v[0:1], v[44:45]
	v_pk_mul_f32 v[30:31], v[2:3], v[30:31]
	v_pk_mul_f32 v[46:47], v[0:1], v[46:47]
	v_pk_mul_f32 v[24:25], v[2:3], v[24:25]
	v_pk_mul_f32 v[26:27], v[26:27], v[42:43]
	v_pk_mul_f32 v[20:21], v[32:33], v[20:21]
	v_pk_mul_f32 v[32:33], v[34:35], v[40:41]
	v_pk_mul_f32 v[12:13], v[12:13], v[28:29]
	v_pk_mul_f32 v[28:29], v[36:37], v[44:45]
	v_pk_mul_f32 v[18:19], v[18:19], v[30:31]
	v_pk_mul_f32 v[30:31], v[38:39], v[46:47]
	v_pk_mul_f32 v[22:23], v[22:23], v[24:25]
	v_cvt_pk_bf16_f32 v24, v26, v27
	v_cvt_pk_bf16_f32 v25, v20, v21
	v_cvt_pk_bf16_f32 v20, v32, v33
	v_cvt_pk_bf16_f32 v21, v12, v13
	v_cvt_pk_bf16_f32 v12, v28, v29
	v_cvt_pk_bf16_f32 v13, v18, v19
	v_cvt_pk_bf16_f32 v18, v30, v31
	v_cvt_pk_bf16_f32 v19, v22, v23
	s_nop 1
	v_mov_b32_dpp v248, v24 quad_perm:[1,0,3,2] row_mask:0xf bank_mask:0xf
	v_mov_b32_dpp v249, v25 quad_perm:[1,0,3,2] row_mask:0xf bank_mask:0xf
	v_mov_b32_dpp v250, v20 quad_perm:[1,0,3,2] row_mask:0xf bank_mask:0xf
	v_mov_b32_dpp v251, v21 quad_perm:[1,0,3,2] row_mask:0xf bank_mask:0xf
	v_cndmask_b32_e64 v240, v24, v250, s[62:63]
	v_cndmask_b32_e64 v241, v25, v251, s[62:63]
	v_cndmask_b32_e64 v242, v248, v20, s[62:63]
	v_cndmask_b32_e64 v243, v249, v21, s[62:63]
	global_store_dwordx4 v[104:105], v[240:243], off offset:2048
	v_mov_b32_dpp v248, v12 quad_perm:[1,0,3,2] row_mask:0xf bank_mask:0xf
	v_mov_b32_dpp v249, v13 quad_perm:[1,0,3,2] row_mask:0xf bank_mask:0xf
	v_mov_b32_dpp v250, v18 quad_perm:[1,0,3,2] row_mask:0xf bank_mask:0xf
	v_mov_b32_dpp v251, v19 quad_perm:[1,0,3,2] row_mask:0xf bank_mask:0xf
	v_cndmask_b32_e64 v240, v12, v250, s[62:63]
	v_cndmask_b32_e64 v241, v13, v251, s[62:63]
	v_cndmask_b32_e64 v242, v248, v18, s[62:63]
	v_cndmask_b32_e64 v243, v249, v19, s[62:63]
	global_store_dwordx4 v[104:105], v[240:243], off offset:3072
	s_cmp_lg_u32 s51, 0
	s_cbranch_scc0 .Lp7n_done
	s_waitcnt vmcnt(2)
	s_branch .LBB0_1053

; __global__ void __launch_bounds__(512, 2) mega_fwd(Args args) {
	.amdhsa_kernel _Z8mega_fwd4Args
		.amdhsa_group_segment_fixed_size 0
		.amdhsa_private_segment_fixed_size 0
		.amdhsa_kernarg_size 536
		.amdhsa_user_sgpr_count 2
		.amdhsa_user_sgpr_dispatch_ptr 0
		.amdhsa_user_sgpr_queue_ptr 0
		.amdhsa_user_sgpr_kernarg_segment_ptr 1
		.amdhsa_user_sgpr_dispatch_id 0
		.amdhsa_user_sgpr_kernarg_preload_length 0
		.amdhsa_user_sgpr_kernarg_preload_offset 0
		.amdhsa_user_sgpr_private_segment_size 0
		.amdhsa_uses_dynamic_stack 0
		.amdhsa_enable_private_segment 0
		.amdhsa_system_sgpr_workgroup_id_x 1
		.amdhsa_system_sgpr_workgroup_id_y 0
		.amdhsa_system_sgpr_workgroup_id_z 0
		.amdhsa_system_sgpr_workgroup_info 0
		.amdhsa_system_vgpr_workitem_id 2
		.amdhsa_next_free_vgpr 256
		.amdhsa_next_free_sgpr 98
		.amdhsa_accum_offset 256
		.amdhsa_reserve_vcc 1
		.amdhsa_float_round_mode_32 0
		.amdhsa_float_round_mode_16_64 0
		.amdhsa_float_denorm_mode_32 3
		.amdhsa_float_denorm_mode_16_64 3
		.amdhsa_dx10_clamp 1
		.amdhsa_ieee_mode 1
		.amdhsa_fp16_overflow 0
		.amdhsa_tg_split 0
		.amdhsa_exception_fp_ieee_invalid_op 0
		.amdhsa_exception_fp_denorm_src 0
		.amdhsa_exception_fp_ieee_div_zero 0
		.amdhsa_exception_fp_ieee_overflow 0
		.amdhsa_exception_fp_ieee_underflow 0
		.amdhsa_exception_fp_ieee_inexact 0
		.amdhsa_exception_int_div_zero 0
	.end_amdhsa_kernel

; __global__ void __launch_bounds__(512, 2) mega_fwd(Args args) {
.Lfunc_end0:
	.size	_Z8mega_fwd4Args, .Lfunc_end0-_Z8mega_fwd4Args
	.set _Z8mega_fwd4Args.num_vgpr, 256
	.set _Z8mega_fwd4Args.num_agpr, 0
	.set _Z8mega_fwd4Args.numbered_sgpr, 98
	.set _Z8mega_fwd4Args.num_named_barrier, 0
	.set _Z8mega_fwd4Args.private_seg_size, 0
	.set _Z8mega_fwd4Args.uses_vcc, 1
	.set _Z8mega_fwd4Args.uses_flat_scratch, 0
	.set _Z8mega_fwd4Args.has_dyn_sized_stack, 0
	.set _Z8mega_fwd4Args.has_recursion, 0
	.set _Z8mega_fwd4Args.has_indirect_call, 0

; __global__ void __launch_bounds__(512, 2) mega_fwd(Args args) {
amdhsa.kernels:
  - .agpr_count:     0
    .args:
      - .offset:         0
        .size:           280
        .value_kind:     by_value
      - .offset:         280
        .size:           4
        .value_kind:     hidden_block_count_x
      - .offset:         284
        .size:           4
        .value_kind:     hidden_block_count_y
      - .offset:         288
        .size:           4
        .value_kind:     hidden_block_count_z
      - .offset:         292
        .size:           2
        .value_kind:     hidden_group_size_x
      - .offset:         294
        .size:           2
        .value_kind:     hidden_group_size_y
      - .offset:         296
        .size:           2
        .value_kind:     hidden_group_size_z
      - .offset:         298
        .size:           2
        .value_kind:     hidden_remainder_x
      - .offset:         300
        .size:           2
        .value_kind:     hidden_remainder_y
      - .offset:         302
        .size:           2
        .value_kind:     hidden_remainder_z
      - .offset:         320
        .size:           8
        .value_kind:     hidden_global_offset_x
      - .offset:         328
        .size:           8
        .value_kind:     hidden_global_offset_y
      - .offset:         336
        .size:           8
        .value_kind:     hidden_global_offset_z
      - .offset:         344
        .size:           2
        .value_kind:     hidden_grid_dims
      - .offset:         368
        .size:           8
        .value_kind:     hidden_multigrid_sync_arg
      - .offset:         400
        .size:           4
        .value_kind:     hidden_dynamic_lds_size
    .group_segment_fixed_size: 0
    .kernarg_segment_align: 8
    .kernarg_segment_size: 536
    .language:       OpenCL C
    .language_version:
      - 2
      - 0
    .max_flat_workgroup_size: 512
    .name:           _Z8mega_fwd4Args
    .private_segment_fixed_size: 0
    .sgpr_count:     104
    .sgpr_spill_count: 73
    .symbol:         _Z8mega_fwd4Args.kd
    .uniform_work_group_size: 1
    .uses_dynamic_stack: false
    .vgpr_count:     256
    .vgpr_spill_count: 0
    .wavefront_size: 64
